# adaLN GEMV task: 64 weight loads in flight at once instead of 4 serialized batches of 16
# baseline (speedup 1.0000x reference)
.LBB0_497:
	s_mul_hi_i32 s8, s3, 0x38e38e39
	s_lshr_b32 s9, s8, 31
	s_ashr_i32 s8, s8, 6
	s_add_i32 s8, s8, s9
	s_mul_i32 s9, s8, 0x120
	s_sub_i32 s9, s3, s9
	v_mad_i64_i32 v[8:9], s[10:11], s8, v244, v[4:5]
	s_lshl_b32 s10, s9, 5
	s_ashr_i32 s11, s10, 31
	v_lshl_add_u64 v[8:9], s[10:11], 2, v[8:9]
	v_mov_b32_e32 v10, 0
	v_lshl_add_u64 v[8:9], v[8:9], 0, v[128:129]
	s_mov_b64 s[12:13], 0
	v_mov_b32_e32 v7, v3
	v_mov_b32_e32 v11, v10
	s_mov_b32 s12, 0x12000
	s_mov_b32 s13, 0
	global_load_dword v130, v[8:9], off
	v_lshl_add_u64 v[14:15], v[8:9], 0, s[12:13]
	global_load_dword v131, v[14:15], off
	v_lshl_add_u64 v[14:15], v[14:15], 0, s[12:13]
	global_load_dword v132, v[14:15], off
	v_lshl_add_u64 v[14:15], v[14:15], 0, s[12:13]
	global_load_dword v133, v[14:15], off
	v_lshl_add_u64 v[14:15], v[14:15], 0, s[12:13]
	global_load_dword v134, v[14:15], off
	v_lshl_add_u64 v[14:15], v[14:15], 0, s[12:13]
	global_load_dword v135, v[14:15], off
	v_lshl_add_u64 v[14:15], v[14:15], 0, s[12:13]
	global_load_dword v136, v[14:15], off
	v_lshl_add_u64 v[14:15], v[14:15], 0, s[12:13]
	global_load_dword v137, v[14:15], off
	v_lshl_add_u64 v[14:15], v[14:15], 0, s[12:13]
	global_load_dword v138, v[14:15], off
	v_lshl_add_u64 v[14:15], v[14:15], 0, s[12:13]
	global_load_dword v139, v[14:15], off
	v_lshl_add_u64 v[14:15], v[14:15], 0, s[12:13]
	global_load_dword v140, v[14:15], off
	v_lshl_add_u64 v[14:15], v[14:15], 0, s[12:13]
	global_load_dword v141, v[14:15], off
	v_lshl_add_u64 v[14:15], v[14:15], 0, s[12:13]
	global_load_dword v142, v[14:15], off
	v_lshl_add_u64 v[14:15], v[14:15], 0, s[12:13]
	global_load_dword v143, v[14:15], off
	v_lshl_add_u64 v[14:15], v[14:15], 0, s[12:13]
	global_load_dword v144, v[14:15], off
	v_lshl_add_u64 v[14:15], v[14:15], 0, s[12:13]
	global_load_dword v145, v[14:15], off
	v_lshl_add_u64 v[14:15], v[14:15], 0, s[12:13]
	global_load_dword v146, v[14:15], off
	v_lshl_add_u64 v[14:15], v[14:15], 0, s[12:13]
	global_load_dword v147, v[14:15], off
	v_lshl_add_u64 v[14:15], v[14:15], 0, s[12:13]
	global_load_dword v148, v[14:15], off
	v_lshl_add_u64 v[14:15], v[14:15], 0, s[12:13]
	global_load_dword v149, v[14:15], off
	v_lshl_add_u64 v[14:15], v[14:15], 0, s[12:13]
	global_load_dword v150, v[14:15], off
	v_lshl_add_u64 v[14:15], v[14:15], 0, s[12:13]
	global_load_dword v151, v[14:15], off
	v_lshl_add_u64 v[14:15], v[14:15], 0, s[12:13]
	global_load_dword v152, v[14:15], off
	v_lshl_add_u64 v[14:15], v[14:15], 0, s[12:13]
	global_load_dword v153, v[14:15], off
	v_lshl_add_u64 v[14:15], v[14:15], 0, s[12:13]
	global_load_dword v154, v[14:15], off
	v_lshl_add_u64 v[14:15], v[14:15], 0, s[12:13]
	global_load_dword v155, v[14:15], off
	v_lshl_add_u64 v[14:15], v[14:15], 0, s[12:13]
	global_load_dword v156, v[14:15], off
	v_lshl_add_u64 v[14:15], v[14:15], 0, s[12:13]
	global_load_dword v157, v[14:15], off
	v_lshl_add_u64 v[14:15], v[14:15], 0, s[12:13]
	global_load_dword v158, v[14:15], off
	v_lshl_add_u64 v[14:15], v[14:15], 0, s[12:13]
	global_load_dword v159, v[14:15], off
	v_lshl_add_u64 v[14:15], v[14:15], 0, s[12:13]
	global_load_dword v160, v[14:15], off
	v_lshl_add_u64 v[14:15], v[14:15], 0, s[12:13]
	global_load_dword v161, v[14:15], off
	v_lshl_add_u64 v[14:15], v[14:15], 0, s[12:13]
	global_load_dword v162, v[14:15], off
	v_lshl_add_u64 v[14:15], v[14:15], 0, s[12:13]
	global_load_dword v163, v[14:15], off
	v_lshl_add_u64 v[14:15], v[14:15], 0, s[12:13]
	global_load_dword v164, v[14:15], off
	v_lshl_add_u64 v[14:15], v[14:15], 0, s[12:13]
	global_load_dword v165, v[14:15], off
	v_lshl_add_u64 v[14:15], v[14:15], 0, s[12:13]
	global_load_dword v166, v[14:15], off
	v_lshl_add_u64 v[14:15], v[14:15], 0, s[12:13]
	global_load_dword v167, v[14:15], off
	v_lshl_add_u64 v[14:15], v[14:15], 0, s[12:13]
	global_load_dword v168, v[14:15], off
	v_lshl_add_u64 v[14:15], v[14:15], 0, s[12:13]
	global_load_dword v169, v[14:15], off
	v_lshl_add_u64 v[14:15], v[14:15], 0, s[12:13]
	global_load_dword v170, v[14:15], off
	v_lshl_add_u64 v[14:15], v[14:15], 0, s[12:13]
	global_load_dword v171, v[14:15], off
	v_lshl_add_u64 v[14:15], v[14:15], 0, s[12:13]
	global_load_dword v172, v[14:15], off
	v_lshl_add_u64 v[14:15], v[14:15], 0, s[12:13]
	global_load_dword v173, v[14:15], off
	v_lshl_add_u64 v[14:15], v[14:15], 0, s[12:13]
	global_load_dword v174, v[14:15], off
	v_lshl_add_u64 v[14:15], v[14:15], 0, s[12:13]
	global_load_dword v175, v[14:15], off
	v_lshl_add_u64 v[14:15], v[14:15], 0, s[12:13]
	global_load_dword v176, v[14:15], off
	v_lshl_add_u64 v[14:15], v[14:15], 0, s[12:13]
	global_load_dword v177, v[14:15], off
	v_lshl_add_u64 v[14:15], v[14:15], 0, s[12:13]
	global_load_dword v178, v[14:15], off
	v_lshl_add_u64 v[14:15], v[14:15], 0, s[12:13]
	global_load_dword v179, v[14:15], off
	v_lshl_add_u64 v[14:15], v[14:15], 0, s[12:13]
	global_load_dword v180, v[14:15], off
	v_lshl_add_u64 v[14:15], v[14:15], 0, s[12:13]
	global_load_dword v181, v[14:15], off
	v_lshl_add_u64 v[14:15], v[14:15], 0, s[12:13]
	global_load_dword v182, v[14:15], off
	v_lshl_add_u64 v[14:15], v[14:15], 0, s[12:13]
	global_load_dword v183, v[14:15], off
	v_lshl_add_u64 v[14:15], v[14:15], 0, s[12:13]
	global_load_dword v184, v[14:15], off
	v_lshl_add_u64 v[14:15], v[14:15], 0, s[12:13]
	global_load_dword v185, v[14:15], off
	v_lshl_add_u64 v[14:15], v[14:15], 0, s[12:13]
	global_load_dword v186, v[14:15], off
	v_lshl_add_u64 v[14:15], v[14:15], 0, s[12:13]
	global_load_dword v187, v[14:15], off
	v_lshl_add_u64 v[14:15], v[14:15], 0, s[12:13]
	global_load_dword v188, v[14:15], off
	v_lshl_add_u64 v[14:15], v[14:15], 0, s[12:13]
	global_load_dword v189, v[14:15], off
	v_lshl_add_u64 v[14:15], v[14:15], 0, s[12:13]
	global_load_dword v190, v[14:15], off
	v_lshl_add_u64 v[14:15], v[14:15], 0, s[12:13]
	global_load_dword v191, v[14:15], off
	v_lshl_add_u64 v[14:15], v[14:15], 0, s[12:13]
	global_load_dword v192, v[14:15], off
	v_lshl_add_u64 v[14:15], v[14:15], 0, s[12:13]
	global_load_dword v193, v[14:15], off
	ds_read2st64_b32 v[98:99], v7 offset1:16
	v_add_u32_e32 v7, 8, v7
	ds_read2st64_b32 v[100:101], v7 offset1:16
	v_add_u32_e32 v7, 8, v7
	ds_read2st64_b32 v[102:103], v7 offset1:16
	v_add_u32_e32 v7, 8, v7
	ds_read2st64_b32 v[104:105], v7 offset1:16
	v_add_u32_e32 v7, 8, v7
	ds_read2st64_b32 v[106:107], v7 offset1:16
	v_add_u32_e32 v7, 8, v7
	ds_read2st64_b32 v[108:109], v7 offset1:16
	v_add_u32_e32 v7, 8, v7
	ds_read2st64_b32 v[110:111], v7 offset1:16
	v_add_u32_e32 v7, 8, v7
	ds_read2st64_b32 v[112:113], v7 offset1:16
	v_add_u32_e32 v7, 8, v7
	s_waitcnt vmcnt(56) lgkmcnt(0)
	v_pk_fma_f32 v[10:11], v[130:131], v[98:99], v[10:11] op_sel_hi:[0,1,1]
	v_pk_fma_f32 v[10:11], v[130:131], v[100:101], v[10:11] op_sel:[1,0,0]
	v_pk_fma_f32 v[10:11], v[132:133], v[102:103], v[10:11] op_sel_hi:[0,1,1]
	v_pk_fma_f32 v[10:11], v[132:133], v[104:105], v[10:11] op_sel:[1,0,0]
	v_pk_fma_f32 v[10:11], v[134:135], v[106:107], v[10:11] op_sel_hi:[0,1,1]
	v_pk_fma_f32 v[10:11], v[134:135], v[108:109], v[10:11] op_sel:[1,0,0]
	v_pk_fma_f32 v[10:11], v[136:137], v[110:111], v[10:11] op_sel_hi:[0,1,1]
	v_pk_fma_f32 v[10:11], v[136:137], v[112:113], v[10:11] op_sel:[1,0,0]
	ds_read2st64_b32 v[98:99], v7 offset1:16
	v_add_u32_e32 v7, 8, v7
	ds_read2st64_b32 v[100:101], v7 offset1:16
	v_add_u32_e32 v7, 8, v7
	ds_read2st64_b32 v[102:103], v7 offset1:16
	v_add_u32_e32 v7, 8, v7
	ds_read2st64_b32 v[104:105], v7 offset1:16
	v_add_u32_e32 v7, 8, v7
	ds_read2st64_b32 v[106:107], v7 offset1:16
	v_add_u32_e32 v7, 8, v7
	ds_read2st64_b32 v[108:109], v7 offset1:16
	v_add_u32_e32 v7, 8, v7
	ds_read2st64_b32 v[110:111], v7 offset1:16
	v_add_u32_e32 v7, 8, v7
	ds_read2st64_b32 v[112:113], v7 offset1:16
	v_add_u32_e32 v7, 8, v7
	s_waitcnt vmcnt(48) lgkmcnt(0)
	v_pk_fma_f32 v[10:11], v[138:139], v[98:99], v[10:11] op_sel_hi:[0,1,1]
	v_pk_fma_f32 v[10:11], v[138:139], v[100:101], v[10:11] op_sel:[1,0,0]
	v_pk_fma_f32 v[10:11], v[140:141], v[102:103], v[10:11] op_sel_hi:[0,1,1]
	v_pk_fma_f32 v[10:11], v[140:141], v[104:105], v[10:11] op_sel:[1,0,0]
	v_pk_fma_f32 v[10:11], v[142:143], v[106:107], v[10:11] op_sel_hi:[0,1,1]
	v_pk_fma_f32 v[10:11], v[142:143], v[108:109], v[10:11] op_sel:[1,0,0]
	v_pk_fma_f32 v[10:11], v[144:145], v[110:111], v[10:11] op_sel_hi:[0,1,1]
	v_pk_fma_f32 v[10:11], v[144:145], v[112:113], v[10:11] op_sel:[1,0,0]
	ds_read2st64_b32 v[98:99], v7 offset1:16
	v_add_u32_e32 v7, 8, v7
	ds_read2st64_b32 v[100:101], v7 offset1:16
	v_add_u32_e32 v7, 8, v7
	ds_read2st64_b32 v[102:103], v7 offset1:16
	v_add_u32_e32 v7, 8, v7
	ds_read2st64_b32 v[104:105], v7 offset1:16
	v_add_u32_e32 v7, 8, v7
	ds_read2st64_b32 v[106:107], v7 offset1:16
	v_add_u32_e32 v7, 8, v7
	ds_read2st64_b32 v[108:109], v7 offset1:16
	v_add_u32_e32 v7, 8, v7
	ds_read2st64_b32 v[110:111], v7 offset1:16
	v_add_u32_e32 v7, 8, v7
	ds_read2st64_b32 v[112:113], v7 offset1:16
	v_add_u32_e32 v7, 8, v7
	s_waitcnt vmcnt(40) lgkmcnt(0)
	v_pk_fma_f32 v[10:11], v[146:147], v[98:99], v[10:11] op_sel_hi:[0,1,1]
	v_pk_fma_f32 v[10:11], v[146:147], v[100:101], v[10:11] op_sel:[1,0,0]
	v_pk_fma_f32 v[10:11], v[148:149], v[102:103], v[10:11] op_sel_hi:[0,1,1]
	v_pk_fma_f32 v[10:11], v[148:149], v[104:105], v[10:11] op_sel:[1,0,0]
	v_pk_fma_f32 v[10:11], v[150:151], v[106:107], v[10:11] op_sel_hi:[0,1,1]
	v_pk_fma_f32 v[10:11], v[150:151], v[108:109], v[10:11] op_sel:[1,0,0]
	v_pk_fma_f32 v[10:11], v[152:153], v[110:111], v[10:11] op_sel_hi:[0,1,1]
	v_pk_fma_f32 v[10:11], v[152:153], v[112:113], v[10:11] op_sel:[1,0,0]
	ds_read2st64_b32 v[98:99], v7 offset1:16
	v_add_u32_e32 v7, 8, v7
	ds_read2st64_b32 v[100:101], v7 offset1:16
	v_add_u32_e32 v7, 8, v7
	ds_read2st64_b32 v[102:103], v7 offset1:16
	v_add_u32_e32 v7, 8, v7
	ds_read2st64_b32 v[104:105], v7 offset1:16
	v_add_u32_e32 v7, 8, v7
	ds_read2st64_b32 v[106:107], v7 offset1:16
	v_add_u32_e32 v7, 8, v7
	ds_read2st64_b32 v[108:109], v7 offset1:16
	v_add_u32_e32 v7, 8, v7
	ds_read2st64_b32 v[110:111], v7 offset1:16
	v_add_u32_e32 v7, 8, v7
	ds_read2st64_b32 v[112:113], v7 offset1:16
	v_add_u32_e32 v7, 8, v7
	s_waitcnt vmcnt(32) lgkmcnt(0)
	v_pk_fma_f32 v[10:11], v[154:155], v[98:99], v[10:11] op_sel_hi:[0,1,1]
	v_pk_fma_f32 v[10:11], v[154:155], v[100:101], v[10:11] op_sel:[1,0,0]
	v_pk_fma_f32 v[10:11], v[156:157], v[102:103], v[10:11] op_sel_hi:[0,1,1]
	v_pk_fma_f32 v[10:11], v[156:157], v[104:105], v[10:11] op_sel:[1,0,0]
	v_pk_fma_f32 v[10:11], v[158:159], v[106:107], v[10:11] op_sel_hi:[0,1,1]
	v_pk_fma_f32 v[10:11], v[158:159], v[108:109], v[10:11] op_sel:[1,0,0]
	v_pk_fma_f32 v[10:11], v[160:161], v[110:111], v[10:11] op_sel_hi:[0,1,1]
	v_pk_fma_f32 v[10:11], v[160:161], v[112:113], v[10:11] op_sel:[1,0,0]
	ds_read2st64_b32 v[98:99], v7 offset1:16
	v_add_u32_e32 v7, 8, v7
	ds_read2st64_b32 v[100:101], v7 offset1:16
	v_add_u32_e32 v7, 8, v7
	ds_read2st64_b32 v[102:103], v7 offset1:16
	v_add_u32_e32 v7, 8, v7
	ds_read2st64_b32 v[104:105], v7 offset1:16
	v_add_u32_e32 v7, 8, v7
	ds_read2st64_b32 v[106:107], v7 offset1:16
	v_add_u32_e32 v7, 8, v7
	ds_read2st64_b32 v[108:109], v7 offset1:16
	v_add_u32_e32 v7, 8, v7
	ds_read2st64_b32 v[110:111], v7 offset1:16
	v_add_u32_e32 v7, 8, v7
	ds_read2st64_b32 v[112:113], v7 offset1:16
	v_add_u32_e32 v7, 8, v7
	s_waitcnt vmcnt(24) lgkmcnt(0)
	v_pk_fma_f32 v[10:11], v[162:163], v[98:99], v[10:11] op_sel_hi:[0,1,1]
	v_pk_fma_f32 v[10:11], v[162:163], v[100:101], v[10:11] op_sel:[1,0,0]
	v_pk_fma_f32 v[10:11], v[164:165], v[102:103], v[10:11] op_sel_hi:[0,1,1]
	v_pk_fma_f32 v[10:11], v[164:165], v[104:105], v[10:11] op_sel:[1,0,0]
	v_pk_fma_f32 v[10:11], v[166:167], v[106:107], v[10:11] op_sel_hi:[0,1,1]
	v_pk_fma_f32 v[10:11], v[166:167], v[108:109], v[10:11] op_sel:[1,0,0]
	v_pk_fma_f32 v[10:11], v[168:169], v[110:111], v[10:11] op_sel_hi:[0,1,1]
	v_pk_fma_f32 v[10:11], v[168:169], v[112:113], v[10:11] op_sel:[1,0,0]
	ds_read2st64_b32 v[98:99], v7 offset1:16
	v_add_u32_e32 v7, 8, v7
	ds_read2st64_b32 v[100:101], v7 offset1:16
	v_add_u32_e32 v7, 8, v7
	ds_read2st64_b32 v[102:103], v7 offset1:16
	v_add_u32_e32 v7, 8, v7
	ds_read2st64_b32 v[104:105], v7 offset1:16
	v_add_u32_e32 v7, 8, v7
	ds_read2st64_b32 v[106:107], v7 offset1:16
	v_add_u32_e32 v7, 8, v7
	ds_read2st64_b32 v[108:109], v7 offset1:16
	v_add_u32_e32 v7, 8, v7
	ds_read2st64_b32 v[110:111], v7 offset1:16
	v_add_u32_e32 v7, 8, v7
	ds_read2st64_b32 v[112:113], v7 offset1:16
	v_add_u32_e32 v7, 8, v7
	s_waitcnt vmcnt(16) lgkmcnt(0)
	v_pk_fma_f32 v[10:11], v[170:171], v[98:99], v[10:11] op_sel_hi:[0,1,1]
	v_pk_fma_f32 v[10:11], v[170:171], v[100:101], v[10:11] op_sel:[1,0,0]
	v_pk_fma_f32 v[10:11], v[172:173], v[102:103], v[10:11] op_sel_hi:[0,1,1]
	v_pk_fma_f32 v[10:11], v[172:173], v[104:105], v[10:11] op_sel:[1,0,0]
	v_pk_fma_f32 v[10:11], v[174:175], v[106:107], v[10:11] op_sel_hi:[0,1,1]
	v_pk_fma_f32 v[10:11], v[174:175], v[108:109], v[10:11] op_sel:[1,0,0]
	v_pk_fma_f32 v[10:11], v[176:177], v[110:111], v[10:11] op_sel_hi:[0,1,1]
	v_pk_fma_f32 v[10:11], v[176:177], v[112:113], v[10:11] op_sel:[1,0,0]
	ds_read2st64_b32 v[98:99], v7 offset1:16
	v_add_u32_e32 v7, 8, v7
	ds_read2st64_b32 v[100:101], v7 offset1:16
	v_add_u32_e32 v7, 8, v7
	ds_read2st64_b32 v[102:103], v7 offset1:16
	v_add_u32_e32 v7, 8, v7
	ds_read2st64_b32 v[104:105], v7 offset1:16
	v_add_u32_e32 v7, 8, v7
	ds_read2st64_b32 v[106:107], v7 offset1:16
	v_add_u32_e32 v7, 8, v7
	ds_read2st64_b32 v[108:109], v7 offset1:16
	v_add_u32_e32 v7, 8, v7
	ds_read2st64_b32 v[110:111], v7 offset1:16
	v_add_u32_e32 v7, 8, v7
	ds_read2st64_b32 v[112:113], v7 offset1:16
	v_add_u32_e32 v7, 8, v7
	s_waitcnt vmcnt(8) lgkmcnt(0)
	v_pk_fma_f32 v[10:11], v[178:179], v[98:99], v[10:11] op_sel_hi:[0,1,1]
	v_pk_fma_f32 v[10:11], v[178:179], v[100:101], v[10:11] op_sel:[1,0,0]
	v_pk_fma_f32 v[10:11], v[180:181], v[102:103], v[10:11] op_sel_hi:[0,1,1]
	v_pk_fma_f32 v[10:11], v[180:181], v[104:105], v[10:11] op_sel:[1,0,0]
	v_pk_fma_f32 v[10:11], v[182:183], v[106:107], v[10:11] op_sel_hi:[0,1,1]
	v_pk_fma_f32 v[10:11], v[182:183], v[108:109], v[10:11] op_sel:[1,0,0]
	v_pk_fma_f32 v[10:11], v[184:185], v[110:111], v[10:11] op_sel_hi:[0,1,1]
	v_pk_fma_f32 v[10:11], v[184:185], v[112:113], v[10:11] op_sel:[1,0,0]
	ds_read2st64_b32 v[98:99], v7 offset1:16
	v_add_u32_e32 v7, 8, v7
	ds_read2st64_b32 v[100:101], v7 offset1:16
	v_add_u32_e32 v7, 8, v7
	ds_read2st64_b32 v[102:103], v7 offset1:16
	v_add_u32_e32 v7, 8, v7
	ds_read2st64_b32 v[104:105], v7 offset1:16
	v_add_u32_e32 v7, 8, v7
	ds_read2st64_b32 v[106:107], v7 offset1:16
	v_add_u32_e32 v7, 8, v7
	ds_read2st64_b32 v[108:109], v7 offset1:16
	v_add_u32_e32 v7, 8, v7
	ds_read2st64_b32 v[110:111], v7 offset1:16
	v_add_u32_e32 v7, 8, v7
	ds_read2st64_b32 v[112:113], v7 offset1:16
	v_add_u32_e32 v7, 8, v7
	s_waitcnt vmcnt(0) lgkmcnt(0)
	v_pk_fma_f32 v[10:11], v[186:187], v[98:99], v[10:11] op_sel_hi:[0,1,1]
	v_pk_fma_f32 v[10:11], v[186:187], v[100:101], v[10:11] op_sel:[1,0,0]
	v_pk_fma_f32 v[10:11], v[188:189], v[102:103], v[10:11] op_sel_hi:[0,1,1]
	v_pk_fma_f32 v[10:11], v[188:189], v[104:105], v[10:11] op_sel:[1,0,0]
	v_pk_fma_f32 v[10:11], v[190:191], v[106:107], v[10:11] op_sel_hi:[0,1,1]
	v_pk_fma_f32 v[10:11], v[190:191], v[108:109], v[10:11] op_sel:[1,0,0]
	v_pk_fma_f32 v[10:11], v[192:193], v[110:111], v[10:11] op_sel_hi:[0,1,1]
	v_pk_fma_f32 v[10:11], v[192:193], v[112:113], v[10:11] op_sel:[1,0,0]
	ds_bpermute_b32 v7, v13, v10
	ds_bpermute_b32 v8, v13, v11
	s_and_saveexec_b64 s[12:13], s[38:39]
	s_cbranch_execz .LBB0_501
	s_waitcnt lgkmcnt(0)
	v_add_f32_e32 v8, v11, v8
	v_add_f32_e32 v7, v10, v7
	ds_write2_b32 v38, v7, v8 offset1:32
